# ret_out-state-loads-issued-after-item-loads-stay-in-flight-during-staging
# baseline (speedup 1.0000x reference)
; #define LAS __attribute__((address_space(3)))
; __device__ __forceinline__ void unpack8(u32x4 u, float* o) { o[0] = bflo(u.x); o[1] = bfhi(u.x); o[2] = bflo(u.y); o[3] = bfhi(u.y); o[4] = bflo(u.z); o[5] = bfhi(u.z); o[6] = bflo(u.w); o[7] = bfhi(u.w); }
; __device__ __forceinline__ u32x4 pack8u(const float* f) { u32x4 u; u.x = pk2(f[0], f[1]); u.y = pk2(f[2], f[3]); u.z = pk2(f[4], f[5]); u.w = pk2(f[6], f[7]); return u; }
; __device__ __forceinline__ void rot8(const bf16* src, const float* rot, int pos, int part, float scale, float* o1, float* o2) {
;     float x1[8], x2[8]; unpack8(*(const u32x4*)(src + 8 * part), x1); unpack8(*(const u32x4*)(src + 32 + 8 * part), x2);
;     const float* cs = rot + (size_t)pos * 32 + 8 * part; const float* sn = rot + (size_t)2048 * 32 + (size_t)pos * 32 + 8 * part;
;     const f32x4 c0 = *(const f32x4*)cs, c1 = *(const f32x4*)(cs + 4), s0 = *(const f32x4*)sn, s1 = *(const f32x4*)(sn + 4);
;     const float cv[8] = {c0.x, c0.y, c0.z, c0.w, c1.x, c1.y, c1.z, c1.w}, sv[8] = {s0.x, s0.y, s0.z, s0.w, s1.x, s1.y, s1.z, s1.w};
; #pragma unroll
;     for (int i = 0; i < 8; ++i) { o1[i] = (x1[i] * cv[i] - x2[i] * sv[i]) * scale; o2[i] = (x1[i] * sv[i] + x2[i] * cv[i]) * scale; }
; }
; __device__ __forceinline__ void ret_out_phase(int l, LAS unsigned char* lds, int wave, int lane_) {
;     ...
;     for (int it = blockIdx.x; it < BATCH * 8 * NRC; it += gridDim.x) {
;         const int j = it % NRC, bh = it / NRC, b = bh >> 3, h = bh & 7;
;         const float l2g = ret_log2g(h);
;         const __amdgpu_buffer_rsrc_t strs = __builtin_amdgcn_make_buffer_rsrc((void*)(ws + OFF_ST), 0, 0x7fffffff, 0x00027000);
;         const unsigned sfo = (unsigned)(((bh * NRC + j) * 2 + 0) * 8192 * 2);
;         u32x4 sfv[4][2], sbv[4][2];
;     ...
;         RET_LD_STATES(0);
;         {
;             const int m = tid >> 2, part = tid & 3; const int pos = j * RC + m;
;             const bf16* src = rawB + ((size_t)b * SEQ + pos) * 2048 + h * 64;
;             float o1[8], o2[8];
;             rot8(src, rot, pos, part, 0.125f, o1, o2);
;             *(LAS u32x4*)(Qs + m * QP + 8 * part) = pack8u(o1); *(LAS u32x4*)(Qs + m * QP + 32 + 8 * part) = pack8u(o2);
;             rot8(src + 512, rot, pos, part, 1.0f, o1, o2);
;             *(LAS u32x4*)(Ks + m * QP + 8 * part) = pack8u(o1); *(LAS u32x4*)(Ks + m * QP + 32 + 8 * part) = pack8u(o2);
.LBB0_632:
	s_ashr_i32 s34, s46, 31
	s_lshr_b32 s34, s34, 28
	s_add_i32 s36, s46, s34
	s_ashr_i32 s37, s36, 4
	s_and_b32 s42, s37, 7
	v_cvt_f32_ubyte0_e32 v4, s42
	v_sub_f32_e32 v4, 0xc0a00000, v4
	v_cmp_gt_f32_e32 vcc, s50, v4
	s_and_b64 s[34:35], vcc, exec
	s_cselect_b32 s34, 0xffffffc0, 0
	v_cndmask_b32_e32 v5, 0, v206, vcc
	v_add_f32_e32 v4, v4, v5
	v_exp_f32_e32 v4, v4
	s_lshl_b32 s35, s37, 11
	v_ldexp_f32 v76, v4, s34
	s_ashr_i32 s34, s36, 7
	s_sub_i32 s36, s29, s35
	v_add_u32_e32 v78, s36, v94
	s_ashr_i32 s35, s34, 31
	s_lshl_b64 s[34:35], s[34:35], 11
	v_ashrrev_i32_e32 v79, 31, v78
	v_lshl_add_u64 v[68:69], s[34:35], 0, v[78:79]
	v_fmamk_f32 v77, v76, 0x3e800000, v201
	v_lshlrev_b64 v[68:69], 12, v[68:69]
	v_pk_mul_f32 v[4:5], v[76:77], v[76:77] op_sel_hi:[0,1]
	v_lshl_add_u64 v[68:69], s[44:45], 0, v[68:69]
	s_lshl_b32 s96, s42, 7
	v_add_f32_e32 v5, 0.5, v5
	v_lshl_add_u64 v[68:69], v[68:69], 0, s[96:97]
	v_fmac_f32_e32 v76, v4, v5
	v_lshl_add_u64 v[90:91], v[68:69], 0, v[2:3]
	v_lshlrev_b64 v[78:79], 7, v[78:79]
	v_lshl_add_u64 v[82:83], v[96:97], 0, v[78:79]
	v_lshl_add_u64 v[110:111], v[98:99], 0, v[78:79]
	s_ashr_i32 s37, s36, 31
	s_add_u32 s34, s34, s36
	s_addc_u32 s35, s35, s37
	s_nop 0
	global_load_dwordx4 v[68:71], v[90:91], off
	global_load_dwordx4 v[72:75], v[90:91], off offset:64
	global_load_dwordx4 v[78:81], v[82:83], off offset:16
	s_nop 0
	global_load_dwordx4 v[82:85], v[82:83], off
	s_nop 0
	global_load_dwordx4 v[86:89], v[110:111], off offset:16
	s_nop 0
	global_load_dwordx4 v[110:113], v[110:111], off
	s_lshl_b32 s96, s42, 8
	v_mov_b32_e32 v109, v3
	s_add_u32 s36, s6, s96
	s_addc_u32 s37, s7, 0
	global_load_dwordx4 v[224:227], v[90:91], off offset:1024
	global_load_dwordx4 v[228:231], v[90:91], off offset:1088
	v_lshl_add_u64 v[248:249], s[34:35], 0, v[94:95]
	v_lshlrev_b64 v[248:249], 12, v[248:249]
	v_lshl_add_u64 v[248:249], s[44:45], 0, v[248:249]
	v_lshl_add_u64 v[248:249], v[248:249], 0, s[96:97]
	v_lshl_add_u64 v[248:249], v[248:249], 0, v[108:109]
	global_load_dwordx4 v[232:235], v[248:249], off offset:2048
	global_load_dwordx4 v[236:239], v[248:249], off offset:2064
	global_load_dwordx4 v[240:243], v[248:249], off offset:2080
	global_load_dwordx4 v[244:247], v[248:249], off offset:2096
	v_add_u32_e32 v12, 0xffff8800, v161
	s_waitcnt vmcnt(17)
	v_add_u32_e32 v20, 0xffffcfc0, v161
	buffer_load_dwordx4 v[16:19], v12, s[60:63], 0 offen sc0 sc1
	s_waitcnt vmcnt(16)
	v_add_u32_e32 v28, 0xffff9000, v161
	buffer_load_dwordx4 v[20:23], v20, s[60:63], 0 offen sc0 sc1
	v_add_u32_e32 v12, 0xffffc800, v161
	v_add_u32_e32 v44, 0xffff9800, v161
	v_add_u32_e32 v52, 0xffffdfc0, v161
	buffer_load_dwordx4 v[24:27], v12, s[60:63], 0 offen sc0 sc1
	buffer_load_dwordx4 v[32:35], v28, s[60:63], 0 offen sc0 sc1
	v_add_u32_e32 v12, 0xffff8fc0, v161
	v_add_u32_e32 v28, 0xffffd000, v161
	buffer_load_dwordx4 v[48:51], v44, s[60:63], 0 offen sc0 sc1
	v_add_u32_e32 v60, 0xffffa000, v161
	buffer_load_dwordx4 v[52:55], v52, s[60:63], 0 offen sc0 sc1
	v_add_u32_e32 v44, 0xffffd800, v161
	v_add_u32_e32 v4, 0xffff87c0, v161
	v_add_u32_e32 v8, 0xffffc7c0, v161
	buffer_load_dwordx4 v[12:15], v12, s[60:63], 0 offen sc0 sc1
	s_waitcnt vmcnt(20)
	v_add_u32_e32 v36, 0xffffd7c0, v161
	buffer_load_dwordx4 v[40:43], v28, s[60:63], 0 offen sc0 sc1
	v_add_u32_e32 v28, 0xffff97c0, v161
	buffer_load_dwordx4 v[56:59], v44, s[60:63], 0 offen sc0 sc1
	v_add_u32_e32 v64, 0xffffe000, v161
	buffer_load_dwordx4 v[60:63], v60, s[60:63], 0 offen sc0 sc1
	v_add_u32_e32 v44, 0xffff9fc0, v161
	buffer_load_dwordx4 v[4:7], v4, s[60:63], 0 offen sc0 sc1
	buffer_load_dwordx4 v[8:11], v8, s[60:63], 0 offen sc0 sc1
	buffer_load_dwordx4 v[28:31], v28, s[60:63], 0 offen sc0 sc1
	buffer_load_dwordx4 v[36:39], v36, s[60:63], 0 offen sc0 sc1
	buffer_load_dwordx4 v[44:47], v44, s[60:63], 0 offen sc0 sc1
	buffer_load_dwordx4 v[64:67], v64, s[60:63], 0 offen sc0 sc1
	s_waitcnt vmcnt(27)
	v_lshlrev_b32_e32 v114, 16, v68
	s_waitcnt vmcnt(26)
	v_lshlrev_b32_e32 v116, 16, v72
	v_and_b32_e32 v117, 0xffff0000, v72
	v_and_b32_e32 v115, 0xffff0000, v68
	s_waitcnt vmcnt(22)
	v_pk_mul_f32 v[182:183], v[110:111], v[116:117]
	v_lshlrev_b32_e32 v72, 16, v73
	v_pk_fma_f32 v[182:183], v[82:83], v[114:115], v[182:183] neg_lo:[0,0,1] neg_hi:[0,0,1]
	v_pk_mul_f32 v[114:115], v[110:111], v[114:115]
	v_and_b32_e32 v73, 0xffff0000, v73
	v_pk_fma_f32 v[114:115], v[82:83], v[116:117], v[114:115]
	v_lshlrev_b32_e32 v68, 16, v69
	v_and_b32_e32 v69, 0xffff0000, v69
	v_pk_mul_f32 v[116:117], v[112:113], v[72:73]
	v_lshlrev_b32_e32 v184, 16, v74
	v_pk_fma_f32 v[116:117], v[84:85], v[68:69], v[116:117] neg_lo:[0,0,1] neg_hi:[0,0,1]
	v_pk_mul_f32 v[68:69], v[112:113], v[68:69]
	v_and_b32_e32 v185, 0xffff0000, v74
	v_pk_fma_f32 v[68:69], v[84:85], v[72:73], v[68:69]
	v_pk_mul_f32 v[186:187], v[86:87], v[184:185]
	v_pk_mul_f32 v[72:73], v[68:69], s[88:89] op_sel_hi:[1,0]
	v_lshlrev_b32_e32 v68, 16, v70
	v_and_b32_e32 v69, 0xffff0000, v70
	v_pk_fma_f32 v[186:187], v[78:79], v[68:69], v[186:187] neg_lo:[0,0,1] neg_hi:[0,0,1]
	v_pk_mul_f32 v[68:69], v[86:87], v[68:69]
	v_lshlrev_b32_e32 v70, 16, v75
	v_pk_fma_f32 v[68:69], v[78:79], v[184:185], v[68:69]
	v_pk_mul_f32 v[182:183], v[182:183], s[88:89] op_sel_hi:[1,0]
	v_pk_mul_f32 v[184:185], v[68:69], s[88:89] op_sel_hi:[1,0]
	v_lshlrev_b32_e32 v68, 16, v71
	v_and_b32_e32 v69, 0xffff0000, v71
	v_and_b32_e32 v71, 0xffff0000, v75
	v_pk_mul_f32 v[74:75], v[88:89], v[70:71]
	v_pk_mul_f32 v[116:117], v[116:117], s[88:89] op_sel_hi:[1,0]
	v_pk_fma_f32 v[74:75], v[80:81], v[68:69], v[74:75] neg_lo:[0,0,1] neg_hi:[0,0,1]
	v_pk_mul_f32 v[68:69], v[88:89], v[68:69]
	v_pk_mul_f32 v[186:187], v[186:187], s[88:89] op_sel_hi:[1,0]
	v_pk_mul_f32 v[74:75], v[74:75], s[88:89] op_sel_hi:[1,0]
	v_pk_fma_f32 v[68:69], v[80:81], v[70:71], v[68:69]
	v_pk_mul_f32 v[114:115], v[114:115], s[88:89] op_sel_hi:[1,0]
	v_pk_mul_f32 v[188:189], v[68:69], s[88:89] op_sel_hi:[1,0]
	v_cvt_pk_bf16_f32 v68, v182, v183
	v_cvt_pk_bf16_f32 v69, v116, v117
	v_cvt_pk_bf16_f32 v70, v186, v187
	v_cvt_pk_bf16_f32 v71, v74, v75
	ds_write_b128 v118, v[68:71]
	v_cvt_pk_bf16_f32 v68, v114, v115
	v_cvt_pk_bf16_f32 v69, v72, v73
	v_cvt_pk_bf16_f32 v70, v184, v185
	v_cvt_pk_bf16_f32 v71, v188, v189
	ds_write_b128 v118, v[68:71] offset:64
	s_waitcnt vmcnt(21)
; #define LAS __attribute__((address_space(3)))
; #define LDS_WAIT() asm volatile("s_waitcnt lgkmcnt(0)" ::: "memory")
; __device__ __forceinline__ unsigned f2bf(float f) { return cvtpk(f, 0.f) & 0xffffu; }
; __device__ __forceinline__ u32x4 pack8u(const float* f) { u32x4 u; u.x = pk2(f[0], f[1]); u.y = pk2(f[2], f[3]); u.z = pk2(f[4], f[5]); u.w = pk2(f[6], f[7]); return u; }
; #define MFMA16(a, b, c) __builtin_amdgcn_mfma_f32_16x16x32_bf16((a), (b), (c), 0, 0, 0)
; __device__ __forceinline__ void stage_vt(const bf16* rawB, int b, int h, int j, LAS bf16* Vt, int tid) {
;     const int m = tid >> 2, part = tid & 3;
;     const bf16* src = rawB + ((size_t)b * SEQ + j * RC + m) * 2048 + 1024 + h * 128 + 32 * part;
; #pragma unroll
;     for (int q = 0; q < 4; ++q) { float f[8]; const u32x4 u = *(const u32x4*)(src + 8 * q);
;         const unsigned w[4] = {u.x, u.y, u.z, u.w};
; #pragma unroll
;         for (int i = 0; i < 4; ++i) { Vt[(32 * part + 8 * q + 2 * i) * KP + m] = (bf16)(w[i] & 0xffffu); Vt[(32 * part + 8 * q + 2 * i + 1) * KP + m] = (bf16)(w[i] >> 16); }
;         (void)f; }
; }
; __device__ __forceinline__ void ret_out_phase(int l, LAS unsigned char* lds, int wave, int lane_) {
;     ...
;             rot8(src + 512, rot, pos, part, 1.0f, o1, o2);
;             *(LAS u32x4*)(Ks + m * QP + 8 * part) = pack8u(o1); *(LAS u32x4*)(Ks + m * QP + 32 + 8 * part) = pack8u(o2);
;             stage_vt(rawB, b, h, j, Vt, tid);
;         }
;         LDS_WAIT(); __syncthreads();
;         bf16x8 aq[2];
; #pragma unroll
;         for (int ks = 0; ks < 2; ++ks) aq[ks] = *(const LAS bf16x8*)(Qs + (16 * wave + fr) * QP + 32 * ks + 8 * fq);
; #pragma unroll
;         for (int nb = 0; nb < 8; ++nb) {
;             f32x4 sc = {0.f, 0.f, 0.f, 0.f};
; #pragma unroll
;             for (int ks = 0; ks < 2; ++ks) { const bf16x8 bk = *(const LAS bf16x8*)(Ks + (nb * 16 + fr) * QP + 32 * ks + 8 * fq); sc = MFMA16(aq[ks], bk, sc); }
; #pragma unroll
;             for (int i = 0; i < 4; ++i) { const int n = 16 * wave + 4 * fq + i, mk = nb * 16 + fr; const int d = n > mk ? n - mk : mk - n;
;                 Pw[(4 * fq + i) * KP + mk] = (bf16)f2bf(sc[i] * __builtin_amdgcn_exp2f(l2g * (float)d)); }
;         }
;         LDS_WAIT(); asm volatile("" ::: "memory");
	v_lshlrev_b32_e32 v90, 16, v224
	s_waitcnt vmcnt(20)
	v_lshlrev_b32_e32 v114, 16, v228
	v_and_b32_e32 v115, 0xffff0000, v228
	v_and_b32_e32 v91, 0xffff0000, v224
	v_pk_mul_f32 v[116:117], v[110:111], v[114:115]
	v_lshlrev_b32_e32 v228, 16, v229
	v_pk_fma_f32 v[116:117], v[82:83], v[90:91], v[116:117] neg_lo:[0,0,1] neg_hi:[0,0,1]
	v_pk_mul_f32 v[82:83], v[82:83], v[114:115]
	v_and_b32_e32 v229, 0xffff0000, v229
	v_pk_fma_f32 v[82:83], v[110:111], v[90:91], v[82:83]
	v_lshlrev_b32_e32 v224, 16, v225
	v_and_b32_e32 v225, 0xffff0000, v225
	v_pk_mul_f32 v[90:91], v[112:113], v[228:229]
	v_pk_mul_f32 v[228:229], v[84:85], v[228:229]
	v_pk_fma_f32 v[90:91], v[84:85], v[224:225], v[90:91] neg_lo:[0,0,1] neg_hi:[0,0,1]
	v_lshlrev_b32_e32 v84, 16, v230
	v_and_b32_e32 v85, 0xffff0000, v230
	v_pk_fma_f32 v[228:229], v[112:113], v[224:225], v[228:229]
	v_lshlrev_b32_e32 v224, 16, v226
	v_and_b32_e32 v225, 0xffff0000, v226
	v_pk_mul_f32 v[110:111], v[86:87], v[84:85]
	v_lshlrev_b32_e32 v226, 16, v231
	v_pk_fma_f32 v[110:111], v[78:79], v[224:225], v[110:111] neg_lo:[0,0,1] neg_hi:[0,0,1]
	v_pk_mul_f32 v[78:79], v[78:79], v[84:85]
	v_mul_f32_e32 v84, 0xbfb8aa3b, v76
	v_pk_fma_f32 v[78:79], v[86:87], v[224:225], v[78:79]
	v_lshlrev_b32_e32 v224, 16, v227
	v_and_b32_e32 v225, 0xffff0000, v227
	v_and_b32_e32 v227, 0xffff0000, v231
	v_pk_mul_f32 v[230:231], v[88:89], v[226:227]
	v_pk_mul_f32 v[226:227], v[80:81], v[226:227]
	v_pk_fma_f32 v[230:231], v[80:81], v[224:225], v[230:231] neg_lo:[0,0,1] neg_hi:[0,0,1]
	v_pk_fma_f32 v[80:81], v[88:89], v[224:225], v[226:227]
	v_cvt_pk_bf16_f32 v224, v116, v117
	v_cvt_pk_bf16_f32 v225, v90, v91
	v_cvt_pk_bf16_f32 v226, v110, v111
	v_cvt_pk_bf16_f32 v227, v230, v231
	ds_write_b128 v118, v[224:227] offset:18432
	v_cvt_pk_bf16_f32 v224, v82, v83
	v_cvt_pk_bf16_f32 v225, v228, v229
	v_cvt_pk_bf16_f32 v226, v78, v79
	v_cvt_pk_bf16_f32 v227, v80, v81
	ds_write_b128 v118, v[224:227] offset:18496
	s_waitcnt vmcnt(19)
	ds_write_b16 v119, v232 offset:36864
	ds_write_b16_d16_hi v119, v232 offset:37136
	ds_write_b16 v119, v233 offset:37408
	ds_write_b16_d16_hi v119, v233 offset:37680
	ds_write_b16 v119, v234 offset:37952
	ds_write_b16_d16_hi v119, v234 offset:38224
	ds_write_b16 v119, v235 offset:38496
	ds_write_b16_d16_hi v119, v235 offset:38768
	s_waitcnt vmcnt(18)
	ds_write_b16 v119, v236 offset:39040
	ds_write_b16_d16_hi v119, v236 offset:39312
	ds_write_b16 v119, v237 offset:39584
	ds_write_b16_d16_hi v119, v237 offset:39856
	ds_write_b16 v119, v238 offset:40128
	ds_write_b16_d16_hi v119, v238 offset:40400
	ds_write_b16 v119, v239 offset:40672
	ds_write_b16_d16_hi v119, v239 offset:40944
	s_waitcnt vmcnt(17)
	ds_write_b16 v119, v240 offset:41216
	ds_write_b16_d16_hi v119, v240 offset:41488
	ds_write_b16 v119, v241 offset:41760
	ds_write_b16_d16_hi v119, v241 offset:42032
	ds_write_b16 v119, v242 offset:42304
	ds_write_b16_d16_hi v119, v242 offset:42576
	ds_write_b16 v119, v243 offset:42848
	ds_write_b16_d16_hi v119, v243 offset:43120
	s_waitcnt vmcnt(16)
	ds_write_b16 v119, v244 offset:43392
	ds_write_b16_d16_hi v119, v244 offset:43664
	ds_write_b16 v119, v245 offset:43936
	ds_write_b16_d16_hi v119, v245 offset:44208
	ds_write_b16 v119, v246 offset:44480
	ds_write_b16_d16_hi v119, v246 offset:44752
	ds_write_b16 v119, v247 offset:45024
	ds_write_b16_d16_hi v119, v247 offset:45296
	s_waitcnt lgkmcnt(0)
	s_waitcnt lgkmcnt(0)
	s_barrier
	ds_read_b128 v[72:75], v162
	ds_read_b128 v[68:71], v162 offset:64
	ds_read_b128 v[76:79], v163 offset:18432
	ds_read_b128 v[80:83], v163 offset:18496
	s_waitcnt lgkmcnt(1)
	v_mfma_f32_16x16x32_bf16 v[76:79], v[72:75], v[76:79], 0
	v_add_u32_e32 v109, 0xffffa7c0, v161
	s_waitcnt lgkmcnt(0)
	v_mfma_f32_16x16x32_bf16 v[76:79], v[68:71], v[80:83], v[76:79]
	v_mul_f32_e32 v80, v84, v121
	v_exp_f32_e32 v80, v80
	s_waitcnt vmcnt(0)
	v_mfma_f32_16x16x32_bf16 v[4:7], v[72:75], v[4:7], 0
	v_mfma_f32_16x16x32_bf16 v[8:11], v[72:75], v[8:11], 0
	s_nop 3
	v_mul_f32_e32 v76, v80, v76
	v_cvt_pk_bf16_f32 v76, v76, s0
	ds_write_b16 v167, v76
	v_mul_f32_e32 v76, v84, v122
	v_exp_f32_e32 v76, v76
	v_mfma_f32_16x16x32_bf16 v[4:7], v[68:71], v[16:19], v[4:7]
	v_mul_f32_e32 v76, v76, v77
	v_cvt_pk_bf16_f32 v76, v76, s0
	ds_write_b16 v167, v76 offset:272
	v_mul_f32_e32 v76, v84, v123
	v_exp_f32_e32 v76, v76
	v_mfma_f32_16x16x32_bf16 v[16:19], v[68:71], v[24:27], v[8:11]
	v_mul_f32_e32 v76, v76, v78
	v_cvt_pk_bf16_f32 v76, v76, s0
	ds_write_b16 v167, v76 offset:544
	v_mul_f32_e32 v76, v84, v124
	v_exp_f32_e32 v76, v76
	v_mfma_f32_16x16x32_bf16 v[10:13], v[72:75], v[12:15], 0
	v_mul_f32_e32 v76, v76, v79
	v_cvt_pk_bf16_f32 v76, v76, s0
	ds_write_b16 v167, v76 offset:816
	ds_read_b128 v[76:79], v163 offset:20736
	ds_read_b128 v[80:83], v163 offset:20800
	s_waitcnt lgkmcnt(1)
	v_mfma_f32_16x16x32_bf16 v[76:79], v[72:75], v[76:79], 0
	s_waitcnt lgkmcnt(0)
	v_mfma_f32_16x16x32_bf16 v[76:79], v[68:71], v[80:83], v[76:79]
	v_mul_f32_e32 v80, v84, v125
	v_exp_f32_e32 v80, v80
	v_mfma_f32_16x16x32_bf16 v[10:13], v[68:71], v[32:35], v[10:13]
	s_nop 4
	v_mul_f32_e32 v76, v80, v76
	v_cvt_pk_bf16_f32 v76, v76, s0
	ds_write_b16 v167, v76 offset:32
	v_mul_f32_e32 v76, v84, v126
	v_exp_f32_e32 v76, v76
	s_nop 0
	v_mul_f32_e32 v76, v76, v77
	v_cvt_pk_bf16_f32 v76, v76, s0
	ds_write_b16 v167, v76 offset:304
	v_mul_f32_e32 v76, v84, v127
	v_exp_f32_e32 v76, v76
	s_nop 0
	v_mul_f32_e32 v76, v76, v78
	v_cvt_pk_bf16_f32 v76, v76, s0
	ds_write_b16 v167, v76 offset:576
	v_mul_f32_e32 v76, v84, v128
	v_exp_f32_e32 v76, v76
	s_nop 0
	v_mul_f32_e32 v76, v76, v79
	v_cvt_pk_bf16_f32 v76, v76, s0
	ds_write_b16 v167, v76 offset:848
	ds_read_b128 v[76:79], v163 offset:23040
	ds_read_b128 v[80:83], v163 offset:23104
	s_waitcnt lgkmcnt(1)
; #define LAS __attribute__((address_space(3)))
; #define LDS_WAIT() asm volatile("s_waitcnt lgkmcnt(0)" ::: "memory")
; __device__ __forceinline__ unsigned f2bf(float f) { return cvtpk(f, 0.f) & 0xffffu; }
; #define MFMA16(a, b, c) __builtin_amdgcn_mfma_f32_16x16x32_bf16((a), (b), (c), 0, 0, 0)
; __device__ __forceinline__ void ret_out_phase(int l, LAS unsigned char* lds, int wave, int lane_) {
;     ...
;         for (int nb = 0; nb < 8; ++nb) {
;             f32x4 sc = {0.f, 0.f, 0.f, 0.f};
; #pragma unroll
;             for (int ks = 0; ks < 2; ++ks) { const bf16x8 bk = *(const LAS bf16x8*)(Ks + (nb * 16 + fr) * QP + 32 * ks + 8 * fq); sc = MFMA16(aq[ks], bk, sc); }
; #pragma unroll
;             for (int i = 0; i < 4; ++i) { const int n = 16 * wave + 4 * fq + i, mk = nb * 16 + fr; const int d = n > mk ? n - mk : mk - n;
;                 Pw[(4 * fq + i) * KP + mk] = (bf16)f2bf(sc[i] * __builtin_amdgcn_exp2f(l2g * (float)d)); }
;         }
;         LDS_WAIT(); asm volatile("" ::: "memory");
;         f32x4 y1[8];
;         f32x4 xfv, xbv;
; #pragma unroll
;         for (int i = 0; i < 4; ++i) { const int nl = 16 * wave + 4 * fq + i; xfv[i] = __builtin_amdgcn_exp2f(l2g * (float)(nl + 1)); xbv[i] = __builtin_amdgcn_exp2f(l2g * (float)(RC - nl)); }
	v_mfma_f32_16x16x32_bf16 v[76:79], v[72:75], v[76:79], 0
	s_waitcnt lgkmcnt(0)
	v_mfma_f32_16x16x32_bf16 v[76:79], v[68:71], v[80:83], v[76:79]
	v_mul_f32_e32 v80, v84, v129
	v_exp_f32_e32 v80, v80
	s_nop 5
	v_mul_f32_e32 v76, v80, v76
	v_cvt_pk_bf16_f32 v76, v76, s0
	ds_write_b16 v167, v76 offset:64
	v_mul_f32_e32 v76, v84, v130
	v_exp_f32_e32 v76, v76
	s_nop 0
	v_mul_f32_e32 v76, v76, v77
	v_cvt_pk_bf16_f32 v76, v76, s0
	ds_write_b16 v167, v76 offset:336
	v_mul_f32_e32 v76, v84, v131
	v_exp_f32_e32 v76, v76
	s_nop 0
	v_mul_f32_e32 v76, v76, v78
	v_cvt_pk_bf16_f32 v76, v76, s0
	ds_write_b16 v167, v76 offset:608
	v_mul_f32_e32 v76, v84, v132
	v_exp_f32_e32 v76, v76
	s_nop 0
	v_mul_f32_e32 v76, v76, v79
	v_cvt_pk_bf16_f32 v76, v76, s0
	ds_write_b16 v167, v76 offset:880
	ds_read_b128 v[76:79], v163 offset:25344
	ds_read_b128 v[80:83], v163 offset:25408
	s_waitcnt lgkmcnt(1)
	v_mfma_f32_16x16x32_bf16 v[76:79], v[72:75], v[76:79], 0
	s_waitcnt lgkmcnt(0)
	v_mfma_f32_16x16x32_bf16 v[76:79], v[68:71], v[80:83], v[76:79]
	v_mul_f32_e32 v80, v84, v133
	v_exp_f32_e32 v80, v80
	s_nop 5
	v_mul_f32_e32 v76, v80, v76
	v_cvt_pk_bf16_f32 v76, v76, s0
	ds_write_b16 v167, v76 offset:96
	v_mul_f32_e32 v76, v84, v134
	v_exp_f32_e32 v76, v76
	s_nop 0
	v_mul_f32_e32 v76, v76, v77
	v_cvt_pk_bf16_f32 v76, v76, s0
	ds_write_b16 v167, v76 offset:368
	v_mul_f32_e32 v76, v84, v135
	v_exp_f32_e32 v76, v76
	s_nop 0
	v_mul_f32_e32 v76, v76, v78
	v_cvt_pk_bf16_f32 v76, v76, s0
	ds_write_b16 v167, v76 offset:640
	v_mul_f32_e32 v76, v84, v136
	v_exp_f32_e32 v76, v76
	s_nop 0
	v_mul_f32_e32 v76, v76, v79
	v_cvt_pk_bf16_f32 v76, v76, s0
	ds_write_b16 v167, v76 offset:912
	ds_read_b128 v[76:79], v163 offset:27648
	ds_read_b128 v[80:83], v163 offset:27712
	s_waitcnt lgkmcnt(1)
	v_mfma_f32_16x16x32_bf16 v[76:79], v[72:75], v[76:79], 0
	s_waitcnt lgkmcnt(0)
	v_mfma_f32_16x16x32_bf16 v[76:79], v[68:71], v[80:83], v[76:79]
	v_mul_f32_e32 v80, v84, v137
	v_exp_f32_e32 v80, v80
	s_nop 5
	v_mul_f32_e32 v76, v80, v76
	v_cvt_pk_bf16_f32 v76, v76, s0
	ds_write_b16 v167, v76 offset:128
	v_mul_f32_e32 v76, v84, v138
	v_exp_f32_e32 v76, v76
	s_nop 0
	v_mul_f32_e32 v76, v76, v77
	v_cvt_pk_bf16_f32 v76, v76, s0
	ds_write_b16 v167, v76 offset:400
	v_mul_f32_e32 v76, v84, v139
	v_exp_f32_e32 v76, v76
	s_nop 0
	v_mul_f32_e32 v76, v76, v78
	v_cvt_pk_bf16_f32 v76, v76, s0
	ds_write_b16 v167, v76 offset:672
	v_mul_f32_e32 v76, v84, v140
	v_exp_f32_e32 v76, v76
	s_nop 0
	v_mul_f32_e32 v76, v76, v79
	v_cvt_pk_bf16_f32 v76, v76, s0
	ds_write_b16 v167, v76 offset:944
	ds_read_b128 v[76:79], v163 offset:29952
	ds_read_b128 v[80:83], v163 offset:30016
	s_waitcnt lgkmcnt(1)
	v_mfma_f32_16x16x32_bf16 v[76:79], v[72:75], v[76:79], 0
	s_waitcnt lgkmcnt(0)
	v_mfma_f32_16x16x32_bf16 v[76:79], v[68:71], v[80:83], v[76:79]
	v_mul_f32_e32 v80, v84, v141
	v_exp_f32_e32 v80, v80
	s_nop 5
	v_mul_f32_e32 v76, v80, v76
	v_cvt_pk_bf16_f32 v76, v76, s0
	ds_write_b16 v167, v76 offset:160
	v_mul_f32_e32 v76, v84, v142
	v_exp_f32_e32 v76, v76
	s_nop 0
	v_mul_f32_e32 v76, v76, v77
	v_cvt_pk_bf16_f32 v76, v76, s0
	ds_write_b16 v167, v76 offset:432
	v_mul_f32_e32 v76, v84, v143
	v_exp_f32_e32 v76, v76
	s_nop 0
	v_mul_f32_e32 v76, v76, v78
	v_cvt_pk_bf16_f32 v76, v76, s0
	ds_write_b16 v167, v76 offset:704
	v_mul_f32_e32 v76, v84, v144
	v_exp_f32_e32 v76, v76
	s_nop 0
	v_mul_f32_e32 v76, v76, v79
	v_cvt_pk_bf16_f32 v76, v76, s0
	ds_write_b16 v167, v76 offset:976
	ds_read_b128 v[76:79], v163 offset:32256
	ds_read_b128 v[80:83], v163 offset:32320
	s_waitcnt lgkmcnt(1)
	v_mfma_f32_16x16x32_bf16 v[76:79], v[72:75], v[76:79], 0
	s_waitcnt lgkmcnt(0)
	v_mfma_f32_16x16x32_bf16 v[76:79], v[68:71], v[80:83], v[76:79]
	v_mul_f32_e32 v80, v84, v145
	v_exp_f32_e32 v80, v80
	s_nop 5
	v_mul_f32_e32 v76, v80, v76
	v_cvt_pk_bf16_f32 v76, v76, s0
	ds_write_b16 v167, v76 offset:192
	v_mul_f32_e32 v76, v84, v146
	v_exp_f32_e32 v76, v76
	s_nop 0
	v_mul_f32_e32 v76, v76, v77
	v_cvt_pk_bf16_f32 v76, v76, s0
	ds_write_b16 v167, v76 offset:464
	v_mul_f32_e32 v76, v84, v147
	v_exp_f32_e32 v76, v76
	s_nop 0
	v_mul_f32_e32 v76, v76, v78
	v_cvt_pk_bf16_f32 v76, v76, s0
	ds_write_b16 v167, v76 offset:736
	v_mul_f32_e32 v76, v84, v148
	v_exp_f32_e32 v76, v76
	s_nop 0
	v_mul_f32_e32 v76, v76, v79
	v_cvt_pk_bf16_f32 v76, v76, s0
	ds_write_b16 v167, v76 offset:1008
	ds_read_b128 v[76:79], v163 offset:34560
	ds_read_b128 v[80:83], v163 offset:34624
	s_waitcnt lgkmcnt(1)
	v_mfma_f32_16x16x32_bf16 v[76:79], v[72:75], v[76:79], 0
	s_waitcnt lgkmcnt(0)
	v_mfma_f32_16x16x32_bf16 v[76:79], v[68:71], v[80:83], v[76:79]
	v_mul_f32_e32 v80, v84, v149
	v_exp_f32_e32 v80, v80
	s_nop 5
	v_mul_f32_e32 v76, v80, v76
	v_cvt_pk_bf16_f32 v76, v76, s0
	ds_write_b16 v167, v76 offset:224
	v_mul_f32_e32 v76, v84, v150
	v_exp_f32_e32 v76, v76
	s_nop 0
	v_mul_f32_e32 v76, v76, v77
	v_cvt_pk_bf16_f32 v76, v76, s0
	ds_write_b16 v167, v76 offset:496
	v_mul_f32_e32 v76, v84, v151
	v_exp_f32_e32 v76, v76
	s_nop 0
	v_mul_f32_e32 v76, v76, v78
	v_cvt_pk_bf16_f32 v76, v76, s0
	ds_write_b16 v167, v76 offset:768
	v_mul_f32_e32 v76, v84, v152
	v_exp_f32_e32 v76, v76
	s_nop 0
	v_mul_f32_e32 v76, v76, v79
	v_cvt_pk_bf16_f32 v76, v76, s0
	ds_write_b16 v167, v76 offset:1040
	v_mul_f32_e32 v76, v84, v153
	v_exp_f32_e32 v112, v76
	v_mul_f32_e32 v76, v84, v154
	v_exp_f32_e32 v110, v76
	v_mul_f32_e32 v76, v84, v155
	v_exp_f32_e32 v113, v76
	v_mul_f32_e32 v76, v84, v156
	v_exp_f32_e32 v111, v76
	v_mul_f32_e32 v76, v84, v157
	v_exp_f32_e32 v116, v76
	v_mul_f32_e32 v76, v84, v158
	v_exp_f32_e32 v114, v76
	v_mul_f32_e32 v76, v84, v159
	s_waitcnt lgkmcnt(0)
; #define LAS __attribute__((address_space(3)))
; #define MFMA16(a, b, c) __builtin_amdgcn_mfma_f32_16x16x32_bf16((a), (b), (c), 0, 0, 0)
; __device__ __forceinline__ void ret_out_phase(int l, LAS unsigned char* lds, int wave, int lane_) {
;     ...
;         for (int i = 0; i < 4; ++i) { const int nl = 16 * wave + 4 * fq + i; xfv[i] = __builtin_amdgcn_exp2f(l2g * (float)(nl + 1)); xbv[i] = __builtin_amdgcn_exp2f(l2g * (float)(RC - nl)); }
;         bf16x8 ap[4];
; #pragma unroll
;         for (int ks = 0; ks < 4; ++ks) ap[ks] = *(const LAS bf16x8*)(Pw + fr * KP + 32 * ks + 8 * fq);
; #pragma unroll
;         for (int g = 0; g < 2; ++g) {
;             if (g == 1) { RET_LD_STATES(1); }
; #pragma unroll
;             for (int o4 = 0; o4 < 4; ++o4) {
;                 const int ob = 4 * g + o4;
;                 f32x4 y2 = {0.f, 0.f, 0.f, 0.f}, y3 = y2; y1[ob] = y2;
; #pragma unroll
;                 for (int ks = 0; ks < 4; ++ks) { const bf16x8 bvv = *(const LAS bf16x8*)(Vt + (ob * 16 + fr) * KP + 32 * ks + 8 * fq); y1[ob] = MFMA16(ap[ks], bvv, y1[ob]); }
; #pragma unroll
;                 for (int ks = 0; ks < 2; ++ks) { y2 = MFMA16(aq[ks], __builtin_bit_cast(bf16x8, sfv[o4][ks]), y2); y3 = MFMA16(aq[ks], __builtin_bit_cast(bf16x8, sbv[o4][ks]), y3); }
;                 y1[ob] = y1[ob] + xfv * y2 + xbv * y3;
;             }
	v_exp_f32_e32 v117, v76
	v_mul_f32_e32 v76, v84, v160
	v_exp_f32_e32 v115, v76
	v_add_u32_e32 v76, v120, v93
	ds_read_b128 v[88:91], v76
	ds_read_b128 v[84:87], v76 offset:64
	ds_read_b128 v[80:83], v76 offset:128
	ds_read_b128 v[76:79], v76 offset:192
	ds_read_b128 v[182:185], v168 offset:36864
	ds_read_b128 v[186:189], v168 offset:36928
	s_waitcnt lgkmcnt(1)
	v_mfma_f32_16x16x32_bf16 v[182:185], v[88:91], v[182:185], 0
	s_waitcnt lgkmcnt(0)
	v_mfma_f32_16x16x32_bf16 v[182:185], v[84:87], v[186:189], v[182:185]
	ds_read_b128 v[186:189], v168 offset:36992
	s_waitcnt lgkmcnt(0)
	v_mfma_f32_16x16x32_bf16 v[182:185], v[80:83], v[186:189], v[182:185]
	ds_read_b128 v[186:189], v168 offset:37056
	s_waitcnt lgkmcnt(0)
	v_mfma_f32_16x16x32_bf16 v[182:185], v[76:79], v[186:189], v[182:185]
	s_nop 7
	v_pk_fma_f32 v[6:7], v[116:117], v[6:7], v[184:185]
	v_pk_fma_f32 v[4:5], v[112:113], v[4:5], v[182:183]
	v_pk_fma_f32 v[8:9], v[114:115], v[18:19], v[6:7]
	v_pk_fma_f32 v[24:25], v[110:111], v[16:17], v[4:5]
	ds_read_b128 v[4:7], v180 offset:36864
	ds_read_b128 v[16:19], v180 offset:36928
	s_waitcnt lgkmcnt(1)
	v_mfma_f32_16x16x32_bf16 v[4:7], v[88:91], v[4:7], 0
	s_waitcnt lgkmcnt(0)
	v_mfma_f32_16x16x32_bf16 v[4:7], v[84:87], v[16:19], v[4:7]
	ds_read_b128 v[16:19], v180 offset:36992
	s_waitcnt lgkmcnt(0)
	v_mfma_f32_16x16x32_bf16 v[4:7], v[80:83], v[16:19], v[4:7]
	ds_read_b128 v[16:19], v180 offset:37056
	s_waitcnt lgkmcnt(0)
	v_mfma_f32_16x16x32_bf16 v[4:7], v[76:79], v[16:19], v[4:7]
	v_mfma_f32_16x16x32_bf16 v[14:17], v[72:75], v[20:23], 0
	s_nop 6
	v_fma_f32 v6, v116, v12, v6
	v_fma_f32 v7, v117, v13, v7
	v_pk_fma_f32 v[4:5], v[112:113], v[10:11], v[4:5]
	v_mfma_f32_16x16x32_bf16 v[14:17], v[68:71], v[40:43], v[14:17]
	s_nop 7
	v_pk_fma_f32 v[10:11], v[114:115], v[16:17], v[6:7]
	v_pk_fma_f32 v[22:23], v[110:111], v[14:15], v[4:5]
	ds_read_b128 v[4:7], v180 offset:41216
	ds_read_b128 v[12:15], v180 offset:41280
	s_waitcnt lgkmcnt(1)
	v_mfma_f32_16x16x32_bf16 v[4:7], v[88:91], v[4:7], 0
	s_waitcnt lgkmcnt(0)
	v_mfma_f32_16x16x32_bf16 v[4:7], v[84:87], v[12:15], v[4:7]
	ds_read_b128 v[12:15], v180 offset:41344
	s_waitcnt lgkmcnt(0)
	v_mfma_f32_16x16x32_bf16 v[4:7], v[80:83], v[12:15], v[4:7]
	ds_read_b128 v[12:15], v180 offset:41408
	s_waitcnt lgkmcnt(0)
	v_mfma_f32_16x16x32_bf16 v[4:7], v[76:79], v[12:15], v[4:7]
	v_mfma_f32_16x16x32_bf16 v[12:15], v[72:75], v[28:31], 0
	v_mfma_f32_16x16x32_bf16 v[16:19], v[72:75], v[36:39], 0
	v_mfma_f32_16x16x32_bf16 v[12:15], v[68:71], v[48:51], v[12:15]
	v_mfma_f32_16x16x32_bf16 v[16:19], v[68:71], v[56:59], v[16:19]
	s_nop 6
	v_fma_f32 v6, v116, v14, v6
	v_fma_f32 v7, v117, v15, v7
	v_pk_fma_f32 v[4:5], v[112:113], v[12:13], v[4:5]
	v_pk_fma_f32 v[12:13], v[114:115], v[18:19], v[6:7]
	v_pk_fma_f32 v[26:27], v[110:111], v[16:17], v[4:5]
	ds_read_b128 v[4:7], v180 offset:45568
	ds_read_b128 v[14:17], v180 offset:45632
	s_waitcnt lgkmcnt(1)
	v_mfma_f32_16x16x32_bf16 v[4:7], v[88:91], v[4:7], 0
	s_waitcnt lgkmcnt(0)
	v_mfma_f32_16x16x32_bf16 v[4:7], v[84:87], v[14:17], v[4:7]
	ds_read_b128 v[14:17], v180 offset:45696
	s_waitcnt lgkmcnt(0)
	v_mfma_f32_16x16x32_bf16 v[4:7], v[80:83], v[14:17], v[4:7]
	ds_read_b128 v[14:17], v180 offset:45760
	s_waitcnt lgkmcnt(0)
	v_mfma_f32_16x16x32_bf16 v[4:7], v[76:79], v[14:17], v[4:7]
	v_mfma_f32_16x16x32_bf16 v[14:17], v[72:75], v[44:47], 0
	v_mfma_f32_16x16x32_bf16 v[18:21], v[72:75], v[52:55], 0
	v_mfma_f32_16x16x32_bf16 v[14:17], v[68:71], v[60:63], v[14:17]
	v_mfma_f32_16x16x32_bf16 v[18:21], v[68:71], v[64:67], v[18:21]
	s_nop 6
	v_fma_f32 v6, v116, v16, v6
	v_fma_f32 v7, v117, v17, v7
	v_pk_fma_f32 v[4:5], v[112:113], v[14:15], v[4:5]
	v_add_u32_e32 v16, 0xffffc000, v161
	v_pk_fma_f32 v[14:15], v[114:115], v[20:21], v[6:7]
	v_pk_fma_f32 v[28:29], v[110:111], v[18:19], v[4:5]
	buffer_load_dwordx4 v[4:7], v161, s[60:63], 0 offen sc0 sc1
	buffer_load_dwordx4 v[38:41], v16, s[60:63], 0 offen sc0 sc1
	v_add_u32_e32 v16, 0xffffbfc0, v161
	v_subrev_u32_e32 v17, 64, v161
	buffer_load_dwordx4 v[42:45], v17, s[60:63], 0 offen sc0 sc1
	buffer_load_dwordx4 v[46:49], v16, s[60:63], 0 offen sc0 sc1
	v_add_u32_e32 v16, 0xfffff800, v161
	buffer_load_dwordx4 v[50:53], v16, s[60:63], 0 offen sc0 sc1
	v_add_u32_e32 v16, 0xffffb800, v161
	buffer_load_dwordx4 v[54:57], v16, s[60:63], 0 offen sc0 sc1
	v_add_u32_e32 v16, 0xffffb7c0, v161
	v_add_u32_e32 v17, 0xfffff7c0, v161
	buffer_load_dwordx4 v[58:61], v17, s[60:63], 0 offen sc0 sc1
	buffer_load_dwordx4 v[62:65], v16, s[60:63], 0 offen sc0 sc1
	v_add_u32_e32 v16, 0xfffff000, v161
	buffer_load_dwordx4 v[18:21], v16, s[60:63], 0 offen sc0 sc1
	v_add_u32_e32 v16, 0xffffb000, v161
	buffer_load_dwordx4 v[34:37], v16, s[60:63], 0 offen sc0 sc1
	v_add_u32_e32 v16, 0xffffafc0, v161
	v_add_u32_e32 v17, 0xffffefc0, v161
	buffer_load_dwordx4 v[182:185], v17, s[60:63], 0 offen sc0 sc1
	buffer_load_dwordx4 v[186:189], v16, s[60:63], 0 offen sc0 sc1
	v_add_u32_e32 v16, 0xffffe800, v161
	buffer_load_dwordx4 v[30:33], v16, s[60:63], 0 offen sc0 sc1
	v_add_u32_e32 v16, 0xffffa800, v161
	buffer_load_dwordx4 v[190:193], v16, s[60:63], 0 offen sc0 sc1
	v_add_u32_e32 v16, 0xffffe7c0, v161
	buffer_load_dwordx4 v[194:197], v16, s[60:63], 0 offen sc0 sc1
	buffer_load_dwordx4 v[208:211], v109, s[60:63], 0 offen sc0 sc1
	ds_read_b128 v[212:215], v180 offset:49920
	ds_read_b128 v[216:219], v180 offset:49984
	s_waitcnt lgkmcnt(1)
	v_mfma_f32_16x16x32_bf16 v[212:215], v[88:91], v[212:215], 0
	v_add_u32_e32 v161, s27, v161
	s_waitcnt lgkmcnt(0)
	v_mfma_f32_16x16x32_bf16 v[212:215], v[84:87], v[216:219], v[212:215]
	ds_read_b128 v[216:219], v180 offset:50048
	s_waitcnt vmcnt(1)
; #define LAS __attribute__((address_space(3)))
; #define MFMA16(a, b, c) __builtin_amdgcn_mfma_f32_16x16x32_bf16((a), (b), (c), 0, 0, 0)
; __device__ __forceinline__ void ret_out_phase(int l, LAS unsigned char* lds, int wave, int lane_) {
;     ...
;             if (g == 1) { RET_LD_STATES(1); }
; #pragma unroll
;             for (int o4 = 0; o4 < 4; ++o4) {
;                 const int ob = 4 * g + o4;
;                 f32x4 y2 = {0.f, 0.f, 0.f, 0.f}, y3 = y2; y1[ob] = y2;
; #pragma unroll
;                 for (int ks = 0; ks < 4; ++ks) { const bf16x8 bvv = *(const LAS bf16x8*)(Vt + (ob * 16 + fr) * KP + 32 * ks + 8 * fq); y1[ob] = MFMA16(ap[ks], bvv, y1[ob]); }
; #pragma unroll
;                 for (int ks = 0; ks < 2; ++ks) { y2 = MFMA16(aq[ks], __builtin_bit_cast(bf16x8, sfv[o4][ks]), y2); y3 = MFMA16(aq[ks], __builtin_bit_cast(bf16x8, sbv[o4][ks]), y3); }
;                 y1[ob] = y1[ob] + xfv * y2 + xbv * y3;
;             }
;             asm volatile("" ::: "memory");
;         }
; #pragma unroll
;         for (int i = 0; i < 4; ++i) {
;             const int nl = 16 * wave + 4 * fq + i;
;             float v[8]; float s = 0.f;
; #pragma unroll
;             for (int ob = 0; ob < 8; ++ob) { v[ob] = y1[ob][i]; s += v[ob]; }
;             s += __shfl_xor(s, 1); s += __shfl_xor(s, 2); s += __shfl_xor(s, 4); s += __shfl_xor(s, 8);
;             const float mean = s * (1.f / 128.f); float q = 0.f;
; #pragma unroll
;             for (int ob = 0; ob < 8; ++ob) { v[ob] -= mean; q += v[ob] * v[ob]; }
;             q += __shfl_xor(q, 1); q += __shfl_xor(q, 2); q += __shfl_xor(q, 4); q += __shfl_xor(q, 8);
	v_mfma_f32_16x16x32_bf16 v[194:197], v[72:75], v[194:197], 0
	v_mfma_f32_16x16x32_bf16 v[30:33], v[68:71], v[30:33], v[194:197]
	s_nop 6
	ds_read_b128 v[194:197], v180 offset:54336
	s_waitcnt lgkmcnt(1)
	v_mfma_f32_16x16x32_bf16 v[212:215], v[80:83], v[216:219], v[212:215]
	ds_read_b128 v[216:219], v180 offset:50112
	s_waitcnt vmcnt(0)
	v_mfma_f32_16x16x32_bf16 v[208:211], v[72:75], v[208:211], 0
	v_mfma_f32_16x16x32_bf16 v[186:189], v[72:75], v[186:189], 0
	v_mfma_f32_16x16x32_bf16 v[190:193], v[68:71], v[190:193], v[208:211]
	v_mfma_f32_16x16x32_bf16 v[34:37], v[68:71], v[34:37], v[186:189]
	s_nop 5
	ds_read_b128 v[186:189], v180 offset:58688
	s_waitcnt lgkmcnt(1)
	v_mfma_f32_16x16x32_bf16 v[212:215], v[76:79], v[216:219], v[212:215]
	v_mfma_f32_16x16x32_bf16 v[182:185], v[72:75], v[182:185], 0
	v_mfma_f32_16x16x32_bf16 v[182:185], v[68:71], v[18:21], v[182:185]
	s_nop 5
	v_fma_f32 v16, v116, v192, v214
	v_fma_f32 v17, v117, v193, v215
	v_pk_fma_f32 v[66:67], v[112:113], v[190:191], v[212:213]
	ds_read_b128 v[190:193], v180 offset:54272
	s_waitcnt lgkmcnt(0)
	v_mfma_f32_16x16x32_bf16 v[190:193], v[88:91], v[190:193], 0
	v_fma_f32 v16, v114, v32, v16
	v_fma_f32 v17, v115, v33, v17
	v_pk_fma_f32 v[32:33], v[110:111], v[30:31], v[66:67]
	v_mfma_f32_16x16x32_bf16 v[190:193], v[84:87], v[194:197], v[190:193]
	ds_read_b128 v[194:197], v180 offset:54400
	s_waitcnt lgkmcnt(0)
	v_mfma_f32_16x16x32_bf16 v[190:193], v[80:83], v[194:197], v[190:193]
	ds_read_b128 v[194:197], v180 offset:54464
	s_waitcnt lgkmcnt(0)
	v_mfma_f32_16x16x32_bf16 v[190:193], v[76:79], v[194:197], v[190:193]
	v_mfma_f32_16x16x32_bf16 v[62:65], v[72:75], v[62:65], 0
	s_nop 6
	v_fma_f32 v18, v116, v36, v192
	v_fma_f32 v19, v117, v37, v193
	v_pk_fma_f32 v[20:21], v[112:113], v[34:35], v[190:191]
	v_pk_fma_f32 v[18:19], v[114:115], v[184:185], v[18:19]
	v_pk_fma_f32 v[34:35], v[110:111], v[182:183], v[20:21]
	ds_read_b128 v[182:185], v180 offset:58624
	s_waitcnt lgkmcnt(0)
	v_mfma_f32_16x16x32_bf16 v[182:185], v[88:91], v[182:185], 0
	v_mfma_f32_16x16x32_bf16 v[182:185], v[84:87], v[186:189], v[182:185]
	ds_read_b128 v[186:189], v180 offset:58752
	s_waitcnt lgkmcnt(0)
	v_mfma_f32_16x16x32_bf16 v[182:185], v[80:83], v[186:189], v[182:185]
	ds_read_b128 v[186:189], v180 offset:58816
	v_mfma_f32_16x16x32_bf16 v[58:61], v[72:75], v[58:61], 0
	s_waitcnt lgkmcnt(0)
	v_mfma_f32_16x16x32_bf16 v[182:185], v[76:79], v[186:189], v[182:185]
	v_mfma_f32_16x16x32_bf16 v[54:57], v[68:71], v[54:57], v[62:65]
	v_mfma_f32_16x16x32_bf16 v[50:53], v[68:71], v[50:53], v[58:61]
	v_mfma_f32_16x16x32_bf16 v[46:49], v[72:75], v[46:49], 0
	s_nop 5
	v_fma_f32 v20, v116, v56, v184
	v_fma_f32 v21, v117, v57, v185
	v_pk_fma_f32 v[30:31], v[112:113], v[54:55], v[182:183]
	v_pk_fma_f32 v[20:21], v[114:115], v[52:53], v[20:21]
	v_pk_fma_f32 v[36:37], v[110:111], v[50:51], v[30:31]
	ds_read_b128 v[50:53], v180 offset:62976
	ds_read_b128 v[54:57], v180 offset:63040
	s_waitcnt lgkmcnt(1)
	v_mfma_f32_16x16x32_bf16 v[50:53], v[88:91], v[50:53], 0
	v_mov_b32_e32 v61, v36
	s_waitcnt lgkmcnt(0)
	v_mfma_f32_16x16x32_bf16 v[50:53], v[84:87], v[54:57], v[50:53]
	ds_read_b128 v[54:57], v180 offset:63104
	s_waitcnt lgkmcnt(0)
	v_mfma_f32_16x16x32_bf16 v[50:53], v[80:83], v[54:57], v[50:53]
	ds_read_b128 v[54:57], v180 offset:63168
	s_load_dwordx2 s[48:49], s[30:31], 0x90
	v_mfma_f32_16x16x32_bf16 v[42:45], v[72:75], v[42:45], 0
	s_waitcnt lgkmcnt(0)
	s_add_u32 s43, s48, s26
	v_mfma_f32_16x16x32_bf16 v[50:53], v[76:79], v[54:57], v[50:53]
	s_addc_u32 s47, s49, 0
	s_lshl_b32 s42, s42, 9
	s_add_u32 s42, s43, s42
	v_mfma_f32_16x16x32_bf16 v[38:41], v[68:71], v[38:41], v[46:49]
	s_addc_u32 s43, s47, 0
	s_add_i32 s46, s46, s58
	s_add_i32 s29, s29, s28
	v_mfma_f32_16x16x32_bf16 v[4:7], v[68:71], v[4:7], v[42:45]
	s_cmpk_lt_i32 s46, 0x800
	s_nop 2
	v_pk_fma_f32 v[30:31], v[116:117], v[40:41], v[52:53]
	v_pk_fma_f32 v[38:39], v[112:113], v[38:39], v[50:51]
	v_lshlrev_b32_e32 v44, 2, v92
	global_load_dword v55, v44, s[42:43]
	global_load_dword v54, v44, s[42:43] offset:64
	global_load_dword v53, v44, s[42:43] offset:128
	global_load_dword v52, v44, s[42:43] offset:192
	global_load_dword v51, v44, s[42:43] offset:256
	global_load_dword v50, v44, s[42:43] offset:320
	global_load_dword v49, v44, s[42:43] offset:384
	global_load_dword v48, v44, s[42:43] offset:448
	v_pk_add_f32 v[44:45], v[24:25], 0 op_sel_hi:[1,0]
	v_pk_fma_f32 v[38:39], v[110:111], v[4:5], v[38:39]
	v_pk_add_f32 v[44:45], v[44:45], v[22:23]
	v_and_b32_e32 v5, 64, v198
	v_pk_add_f32 v[44:45], v[44:45], v[26:27]
	v_xor_b32_e32 v4, 1, v198
	v_pk_add_f32 v[44:45], v[44:45], v[28:29]
	v_add_u32_e32 v5, 64, v5
	v_pk_add_f32 v[44:45], v[44:45], v[32:33]
	v_cmp_lt_i32_e32 vcc, v4, v5
	v_pk_add_f32 v[44:45], v[44:45], v[34:35]
	v_pk_fma_f32 v[6:7], v[114:115], v[6:7], v[30:31]
	v_cndmask_b32_e32 v4, v198, v4, vcc
	v_mov_b32_e32 v30, v28
	v_mov_b32_e32 v31, v26
	v_mov_b32_e32 v26, v29
	v_pk_add_f32 v[28:29], v[44:45], v[36:37]
	v_lshlrev_b32_e32 v56, 2, v4
	v_pk_add_f32 v[28:29], v[28:29], v[38:39]
	ds_bpermute_b32 v44, v56, v28
	ds_bpermute_b32 v45, v56, v29
	v_xor_b32_e32 v4, 2, v198
	v_cmp_lt_i32_e32 vcc, v4, v5
	v_mov_b32_e32 v42, v34
	v_mov_b32_e32 v43, v32
	v_cndmask_b32_e32 v4, v198, v4, vcc
	v_lshlrev_b32_e32 v57, 2, v4
	s_waitcnt lgkmcnt(0)
	v_pk_add_f32 v[28:29], v[28:29], v[44:45]
	ds_bpermute_b32 v44, v57, v28
	ds_bpermute_b32 v45, v57, v29
	v_xor_b32_e32 v4, 4, v198
	v_cmp_lt_i32_e32 vcc, v4, v5
	v_mov_b32_e32 v32, v35
	v_mov_b32_e32 v36, v39
	v_cndmask_b32_e32 v4, v198, v4, vcc
	v_lshlrev_b32_e32 v58, 2, v4
	s_waitcnt lgkmcnt(0)
; __device__ __forceinline__ unsigned f2bf(float f) { return cvtpk(f, 0.f) & 0xffffu; }
; __device__ __forceinline__ void ret_out_phase(int l, LAS unsigned char* lds, int wave, int lane_) {
;     ...
;         for (int i = 0; i < 4; ++i) {
;             const int nl = 16 * wave + 4 * fq + i;
;             float v[8]; float s = 0.f;
; #pragma unroll
;             for (int ob = 0; ob < 8; ++ob) { v[ob] = y1[ob][i]; s += v[ob]; }
;             s += __shfl_xor(s, 1); s += __shfl_xor(s, 2); s += __shfl_xor(s, 4); s += __shfl_xor(s, 8);
;             const float mean = s * (1.f / 128.f); float q = 0.f;
; #pragma unroll
;             for (int ob = 0; ob < 8; ++ob) { v[ob] -= mean; q += v[ob] * v[ob]; }
;             q += __shfl_xor(q, 1); q += __shfl_xor(q, 2); q += __shfl_xor(q, 4); q += __shfl_xor(q, 8);
;             const float rstd = rsqrtf(q * (1.f / 128.f) + 1e-6f);
;             bf16* yo = (bf16*)(ws + OFF_YB) + ((size_t)b * SEQ + j * RC + nl) * DM + h * 128;
;             const float* gn = p->in[I_RG] + (size_t)l * DM + h * 128;
; #pragma unroll
;             for (int ob = 0; ob < 8; ++ob) yo[ob * 16 + fr] = (bf16)f2bf(v[ob] * rstd * gn[ob * 16 + fr]);
	v_pk_add_f32 v[28:29], v[28:29], v[44:45]
	ds_bpermute_b32 v44, v58, v28
	ds_bpermute_b32 v45, v58, v29
	v_xor_b32_e32 v4, 8, v198
	v_cmp_lt_i32_e32 vcc, v4, v5
	v_mov_b32_e32 v60, v38
	s_mov_b32 s42, 0x358637bd
	v_cndmask_b32_e32 v4, v198, v4, vcc
	v_lshlrev_b32_e32 v59, 2, v4
	s_waitcnt lgkmcnt(0)
	v_pk_add_f32 v[28:29], v[28:29], v[44:45]
	ds_bpermute_b32 v44, v59, v28
	ds_bpermute_b32 v45, v59, v29
	v_lshl_add_u64 v[4:5], s[34:35], 0, v[100:101]
	v_lshlrev_b64 v[4:5], 11, v[4:5]
	v_lshl_add_u64 v[40:41], s[36:37], 0, v[4:5]
	v_lshlrev_b32_e32 v4, 1, v92
	s_waitcnt lgkmcnt(0)
	v_pk_add_f32 v[28:29], v[28:29], v[44:45]
	v_mov_b32_e32 v5, v3
	v_pk_mul_f32 v[62:63], v[28:29], s[86:87] op_sel_hi:[1,0]
	v_lshl_add_u64 v[40:41], v[40:41], 0, v[4:5]
	v_pk_add_f32 v[46:47], v[30:31], v[62:63] op_sel_hi:[1,0] neg_lo:[0,1] neg_hi:[0,1]
	v_pk_fma_f32 v[30:31], v[28:29], s[86:87], v[24:25] op_sel_hi:[1,0,1] neg_lo:[1,0,0] neg_hi:[1,0,0]
	v_pk_fma_f32 v[28:29], v[28:29], s[86:87], v[22:23] op_sel_hi:[1,0,1] neg_lo:[1,0,0] neg_hi:[1,0,0]
	v_pk_add_f32 v[26:27], v[26:27], v[62:63] op_sel:[0,1] neg_lo:[0,1] neg_hi:[0,1]
	v_pk_mul_f32 v[64:65], v[46:47], v[46:47]
	v_pk_mul_f32 v[22:23], v[28:29], v[28:29]
	v_pk_mul_f32 v[70:71], v[26:27], v[26:27]
	v_pk_add_f32 v[44:45], v[42:43], v[62:63] op_sel_hi:[1,0] neg_lo:[0,1] neg_hi:[0,1]
	v_pk_fma_f32 v[68:69], v[30:31], v[30:31], v[22:23]
	v_pk_add_f32 v[24:25], v[32:33], v[62:63] op_sel:[0,1] neg_lo:[0,1] neg_hi:[0,1]
	v_pk_add_f32 v[22:23], v[36:37], v[62:63] op_sel:[0,1] neg_lo:[0,1] neg_hi:[0,1]
	v_mov_b32_e32 v37, v64
	v_mov_b32_e32 v64, v71
	v_pk_mul_f32 v[66:67], v[44:45], v[44:45]
	v_pk_mul_f32 v[32:33], v[24:25], v[24:25]
	v_mov_b32_e32 v36, v70
	v_pk_add_f32 v[38:39], v[64:65], v[68:69] op_sel:[0,1] op_sel_hi:[1,0]
	v_pk_add_f32 v[42:43], v[60:61], v[62:63] op_sel_hi:[1,0] neg_lo:[0,1] neg_hi:[0,1]
	v_pk_add_f32 v[36:37], v[36:37], v[38:39]
	v_mov_b32_e32 v38, v33
	v_mov_b32_e32 v39, v67
	v_pk_mul_f32 v[60:61], v[42:43], v[42:43]
	v_pk_mul_f32 v[34:35], v[22:23], v[22:23]
	v_pk_add_f32 v[36:37], v[38:39], v[36:37]
	v_mov_b32_e32 v33, v66
	v_pk_add_f32 v[32:33], v[32:33], v[36:37]
	v_mov_b32_e32 v36, v35
	v_mov_b32_e32 v37, v61
	v_pk_add_f32 v[32:33], v[36:37], v[32:33]
	v_mov_b32_e32 v35, v60
	v_pk_add_f32 v[32:33], v[34:35], v[32:33]
	ds_bpermute_b32 v35, v56, v33
	ds_bpermute_b32 v34, v56, v32
	s_waitcnt lgkmcnt(0)
	v_pk_add_f32 v[32:33], v[32:33], v[34:35]
	ds_bpermute_b32 v35, v57, v33
	ds_bpermute_b32 v34, v57, v32
	s_waitcnt lgkmcnt(0)
	v_pk_add_f32 v[32:33], v[32:33], v[34:35]
	ds_bpermute_b32 v35, v58, v33
	ds_bpermute_b32 v34, v58, v32
	s_waitcnt lgkmcnt(0)
	v_pk_add_f32 v[32:33], v[32:33], v[34:35]
	ds_bpermute_b32 v35, v59, v33
	ds_bpermute_b32 v34, v59, v32
	s_waitcnt lgkmcnt(0)
	v_pk_add_f32 v[34:35], v[32:33], v[34:35]
	v_mov_b64_e32 v[32:33], s[42:43]
	v_pk_fma_f32 v[34:35], v[34:35], s[86:87], v[32:33] op_sel_hi:[1,0,0]
	s_nop 0
	v_mul_f32_e32 v36, 0x4b800000, v35
	v_cmp_gt_f32_e64 s[42:43], s19, v35
	v_cmp_gt_f32_e32 vcc, s19, v34
	s_nop 0
	v_cndmask_b32_e64 v35, v35, v36, s[42:43]
	v_rsq_f32_e32 v35, v35
	s_nop 0
	v_mul_f32_e32 v36, 0x45800000, v35
	v_cndmask_b32_e64 v35, v35, v36, s[42:43]
	v_mul_f32_e32 v28, v28, v35
	s_waitcnt vmcnt(6)
	v_mul_f32_e32 v28, v54, v28
	v_cvt_pk_bf16_f32 v28, v28, s0
	global_store_short v[40:41], v28, off offset:32
	v_mul_f32_e32 v28, v47, v35
	s_waitcnt vmcnt(6)
	v_mul_f32_e32 v28, v53, v28
	v_cvt_pk_bf16_f32 v28, v28, s0
	global_store_short v[40:41], v28, off offset:64
	v_mul_f32_e32 v28, v46, v35
	s_waitcnt vmcnt(6)
	v_mul_f32_e32 v28, v52, v28
	v_cvt_pk_bf16_f32 v28, v28, s0
	global_store_short v[40:41], v28, off offset:96
	v_mul_f32_e32 v28, v45, v35
	s_waitcnt vmcnt(6)
	v_mul_f32_e32 v28, v51, v28
	v_cvt_pk_bf16_f32 v28, v28, s0
	global_store_short v[40:41], v28, off offset:128
	v_mul_f32_e32 v28, v44, v35
	s_waitcnt vmcnt(6)
	v_mul_f32_e32 v28, v50, v28
	v_cvt_pk_bf16_f32 v28, v28, s0
	global_store_short v[40:41], v28, off offset:160
	v_mul_f32_e32 v28, v43, v35
	s_waitcnt vmcnt(6)
	v_mul_f32_e32 v28, v49, v28
	v_cvt_pk_bf16_f32 v28, v28, s0
	global_store_short v[40:41], v28, off offset:192
	v_mul_f32_e32 v28, v42, v35
	s_waitcnt vmcnt(6)
	v_mul_f32_e32 v28, v48, v28
	v_cvt_pk_bf16_f32 v28, v28, s0
	global_store_short v[40:41], v28, off offset:224
	v_mul_f32_e32 v28, 0x4b800000, v34
	v_cndmask_b32_e32 v28, v34, v28, vcc
	v_rsq_f32_e32 v28, v28
	v_mul_f32_e32 v30, v30, v35
	v_mul_f32_e32 v30, v55, v30
	v_cvt_pk_bf16_f32 v30, v30, s0
	global_store_short v[40:41], v30, off
	v_mul_f32_e32 v30, 0x45800000, v28
	v_cndmask_b32_e32 v28, v28, v30, vcc
	v_lshl_add_u64 v[34:35], s[34:35], 0, v[102:103]
	v_lshlrev_b64 v[34:35], 11, v[34:35]
	v_mul_f32_e32 v30, v31, v28
	v_mul_f32_e32 v29, v29, v28
	v_mul_f32_e32 v27, v27, v28
	v_mul_f32_e32 v26, v26, v28
	v_mul_f32_e32 v25, v25, v28
	v_mul_f32_e32 v24, v24, v28
	v_mul_f32_e32 v23, v23, v28
	v_mul_f32_e32 v22, v22, v28
	v_lshl_add_u64 v[34:35], s[36:37], 0, v[34:35]
	v_mul_f32_e32 v30, v55, v30
	v_mul_f32_e32 v29, v54, v29
	v_mul_f32_e32 v27, v53, v27
	v_mul_f32_e32 v26, v52, v26
	v_mul_f32_e32 v25, v51, v25
	v_mul_f32_e32 v24, v50, v24
	v_mul_f32_e32 v23, v49, v23
	v_mul_f32_e32 v22, v48, v22
	v_cvt_pk_bf16_f32 v36, v30, s0
	v_lshl_add_u64 v[30:31], v[34:35], 0, v[4:5]
	v_cvt_pk_bf16_f32 v29, v29, s0
	v_cvt_pk_bf16_f32 v27, v27, s0
	v_cvt_pk_bf16_f32 v26, v26, s0
	v_cvt_pk_bf16_f32 v25, v25, s0
	v_cvt_pk_bf16_f32 v24, v24, s0
	v_cvt_pk_bf16_f32 v23, v23, s0
	v_cvt_pk_bf16_f32 v22, v22, s0
	global_store_short v[30:31], v36, off
	global_store_short v[30:31], v29, off offset:32
	global_store_short v[30:31], v27, off offset:64
	global_store_short v[30:31], v26, off offset:96
	global_store_short v[30:31], v25, off offset:128
	global_store_short v[30:31], v24, off offset:160
	global_store_short v[30:31], v23, off offset:192
	global_store_short v[30:31], v22, off offset:224
	v_pk_add_f32 v[30:31], v[8:9], 0 op_sel_hi:[1,0]
	v_mov_b32_e32 v22, v14
	v_pk_add_f32 v[30:31], v[30:31], v[10:11]
	v_mov_b32_e32 v23, v12
	v_pk_add_f32 v[30:31], v[30:31], v[12:13]
	v_mov_b32_e32 v12, v15
	v_pk_add_f32 v[30:31], v[30:31], v[14:15]
	v_mov_b32_e32 v24, v18
	v_pk_add_f32 v[30:31], v[30:31], v[16:17]
	v_mov_b32_e32 v25, v16
	v_pk_add_f32 v[30:31], v[30:31], v[18:19]
	v_mov_b32_e32 v27, v20
	v_pk_add_f32 v[14:15], v[30:31], v[20:21]
	v_mov_b32_e32 v16, v19
	v_pk_add_f32 v[14:15], v[14:15], v[6:7]
	ds_bpermute_b32 v30, v56, v14
	ds_bpermute_b32 v31, v56, v15
	v_mov_b32_e32 v20, v7
	v_mov_b32_e32 v26, v6
	v_lshl_add_u64 v[28:29], s[34:35], 0, v[104:105]
	v_lshlrev_b64 v[28:29], 11, v[28:29]
	s_waitcnt lgkmcnt(0)
; __device__ __forceinline__ unsigned f2bf(float f) { return cvtpk(f, 0.f) & 0xffffu; }
; __device__ __forceinline__ void ret_out_phase(int l, LAS unsigned char* lds, int wave, int lane_) {
;     ...
;         for (int i = 0; i < 4; ++i) {
;             const int nl = 16 * wave + 4 * fq + i;
;             float v[8]; float s = 0.f;
; #pragma unroll
;             for (int ob = 0; ob < 8; ++ob) { v[ob] = y1[ob][i]; s += v[ob]; }
;             s += __shfl_xor(s, 1); s += __shfl_xor(s, 2); s += __shfl_xor(s, 4); s += __shfl_xor(s, 8);
;             const float mean = s * (1.f / 128.f); float q = 0.f;
; #pragma unroll
;             for (int ob = 0; ob < 8; ++ob) { v[ob] -= mean; q += v[ob] * v[ob]; }
;             q += __shfl_xor(q, 1); q += __shfl_xor(q, 2); q += __shfl_xor(q, 4); q += __shfl_xor(q, 8);
;             const float rstd = rsqrtf(q * (1.f / 128.f) + 1e-6f);
;             bf16* yo = (bf16*)(ws + OFF_YB) + ((size_t)b * SEQ + j * RC + nl) * DM + h * 128;
;             const float* gn = p->in[I_RG] + (size_t)l * DM + h * 128;
; #pragma unroll
;             for (int ob = 0; ob < 8; ++ob) yo[ob * 16 + fr] = (bf16)f2bf(v[ob] * rstd * gn[ob * 16 + fr]);
;         }
;         __syncthreads();
	v_pk_add_f32 v[14:15], v[14:15], v[30:31]
	ds_bpermute_b32 v30, v57, v14
	ds_bpermute_b32 v31, v57, v15
	v_lshl_add_u64 v[28:29], s[36:37], 0, v[28:29]
	v_lshl_add_u64 v[28:29], v[28:29], 0, v[4:5]
	s_waitcnt lgkmcnt(0)
	v_pk_add_f32 v[14:15], v[14:15], v[30:31]
	ds_bpermute_b32 v30, v58, v14
	ds_bpermute_b32 v31, v58, v15
	s_waitcnt lgkmcnt(0)
	v_pk_add_f32 v[14:15], v[14:15], v[30:31]
	ds_bpermute_b32 v30, v59, v14
	ds_bpermute_b32 v31, v59, v15
	s_waitcnt lgkmcnt(0)
	v_pk_add_f32 v[14:15], v[14:15], v[30:31]
	s_nop 0
	v_pk_mul_f32 v[30:31], v[14:15], s[86:87] op_sel_hi:[1,0]
	s_nop 0
	v_pk_add_f32 v[34:35], v[22:23], v[30:31] op_sel_hi:[1,0] neg_lo:[0,1] neg_hi:[0,1]
	v_pk_fma_f32 v[22:23], v[14:15], s[86:87], v[8:9] op_sel_hi:[1,0,1] neg_lo:[1,0,0] neg_hi:[1,0,0]
	v_pk_fma_f32 v[14:15], v[14:15], s[86:87], v[10:11] op_sel_hi:[1,0,1] neg_lo:[1,0,0] neg_hi:[1,0,0]
	v_pk_add_f32 v[10:11], v[12:13], v[30:31] op_sel:[0,1] neg_lo:[0,1] neg_hi:[0,1]
	v_pk_mul_f32 v[36:37], v[34:35], v[34:35]
	v_pk_mul_f32 v[8:9], v[14:15], v[14:15]
	v_pk_mul_f32 v[12:13], v[10:11], v[10:11]
	v_pk_add_f32 v[24:25], v[24:25], v[30:31] op_sel_hi:[1,0] neg_lo:[0,1] neg_hi:[0,1]
	v_pk_fma_f32 v[42:43], v[22:23], v[22:23], v[8:9]
	v_pk_add_f32 v[8:9], v[16:17], v[30:31] op_sel:[0,1] neg_lo:[0,1] neg_hi:[0,1]
	v_pk_add_f32 v[6:7], v[20:21], v[30:31] op_sel:[0,1] neg_lo:[0,1] neg_hi:[0,1]
	v_mov_b32_e32 v21, v36
	v_mov_b32_e32 v36, v13
	v_pk_mul_f32 v[38:39], v[24:25], v[24:25]
	v_pk_mul_f32 v[16:17], v[8:9], v[8:9]
	v_mov_b32_e32 v20, v12
	v_pk_add_f32 v[12:13], v[36:37], v[42:43] op_sel:[0,1] op_sel_hi:[1,0]
	v_pk_add_f32 v[26:27], v[26:27], v[30:31] op_sel_hi:[1,0] neg_lo:[0,1] neg_hi:[0,1]
	v_pk_add_f32 v[12:13], v[20:21], v[12:13]
	v_mov_b32_e32 v20, v17
	v_mov_b32_e32 v21, v39
	v_pk_mul_f32 v[40:41], v[26:27], v[26:27]
	v_pk_mul_f32 v[18:19], v[6:7], v[6:7]
	v_pk_add_f32 v[12:13], v[20:21], v[12:13]
	v_mov_b32_e32 v17, v38
	v_pk_add_f32 v[12:13], v[16:17], v[12:13]
	v_mov_b32_e32 v16, v19
	v_mov_b32_e32 v17, v41
	v_pk_add_f32 v[12:13], v[16:17], v[12:13]
	v_mov_b32_e32 v19, v40
	v_pk_add_f32 v[12:13], v[18:19], v[12:13]
	ds_bpermute_b32 v17, v56, v13
	ds_bpermute_b32 v16, v56, v12
	s_waitcnt lgkmcnt(0)
	v_pk_add_f32 v[12:13], v[12:13], v[16:17]
	ds_bpermute_b32 v17, v57, v13
	ds_bpermute_b32 v16, v57, v12
	s_waitcnt lgkmcnt(0)
	v_pk_add_f32 v[12:13], v[12:13], v[16:17]
	ds_bpermute_b32 v17, v58, v13
	ds_bpermute_b32 v16, v58, v12
	s_waitcnt lgkmcnt(0)
	v_pk_add_f32 v[12:13], v[12:13], v[16:17]
	ds_bpermute_b32 v17, v59, v13
	ds_bpermute_b32 v16, v59, v12
	s_waitcnt lgkmcnt(0)
	v_pk_add_f32 v[12:13], v[12:13], v[16:17]
	s_nop 0
	v_pk_fma_f32 v[12:13], v[12:13], s[86:87], v[32:33] op_sel_hi:[1,0,0]
	s_nop 0
	v_mul_f32_e32 v16, 0x4b800000, v13
	v_cmp_gt_f32_e64 s[42:43], s19, v13
	v_cmp_gt_f32_e32 vcc, s19, v12
	s_nop 0
	v_cndmask_b32_e64 v13, v13, v16, s[42:43]
	v_rsq_f32_e32 v13, v13
	s_nop 0
	v_mul_f32_e32 v16, 0x45800000, v13
	v_cndmask_b32_e64 v13, v13, v16, s[42:43]
	v_mul_f32_e32 v14, v14, v13
	v_mul_f32_e32 v14, v54, v14
	v_cvt_pk_bf16_f32 v14, v14, s0
	global_store_short v[28:29], v14, off offset:32
	v_mul_f32_e32 v14, v35, v13
	v_mul_f32_e32 v14, v53, v14
	v_cvt_pk_bf16_f32 v14, v14, s0
	global_store_short v[28:29], v14, off offset:64
	v_mul_f32_e32 v14, v34, v13
	v_mul_f32_e32 v14, v52, v14
	v_cvt_pk_bf16_f32 v14, v14, s0
	global_store_short v[28:29], v14, off offset:96
	v_mul_f32_e32 v14, v25, v13
	v_mul_f32_e32 v14, v51, v14
	v_cvt_pk_bf16_f32 v14, v14, s0
	global_store_short v[28:29], v14, off offset:128
	v_mul_f32_e32 v14, v24, v13
	v_mul_f32_e32 v14, v50, v14
	v_cvt_pk_bf16_f32 v14, v14, s0
	v_mul_f32_e32 v16, v22, v13
	global_store_short v[28:29], v14, off offset:160
	v_mul_f32_e32 v14, v27, v13
	v_mul_f32_e32 v13, v26, v13
	v_mul_f32_e32 v13, v48, v13
	v_cvt_pk_bf16_f32 v13, v13, s0
	global_store_short v[28:29], v13, off offset:224
	v_mul_f32_e32 v13, 0x4b800000, v12
	v_cndmask_b32_e32 v12, v12, v13, vcc
	v_rsq_f32_e32 v12, v12
	v_mul_f32_e32 v14, v49, v14
	v_cvt_pk_bf16_f32 v14, v14, s0
	global_store_short v[28:29], v14, off offset:192
	v_mul_f32_e32 v13, 0x45800000, v12
	v_cndmask_b32_e32 v14, v12, v13, vcc
	v_lshl_add_u64 v[12:13], s[34:35], 0, v[106:107]
	v_mul_f32_e32 v16, v55, v16
	v_lshlrev_b64 v[12:13], 11, v[12:13]
	v_cvt_pk_bf16_f32 v16, v16, s0
	v_lshl_add_u64 v[12:13], s[36:37], 0, v[12:13]
	global_store_short v[28:29], v16, off
	v_mul_f32_e32 v16, v23, v14
	v_lshl_add_u64 v[4:5], v[12:13], 0, v[4:5]
	v_mul_f32_e32 v12, v15, v14
	v_mul_f32_e32 v11, v11, v14
	v_mul_f32_e32 v10, v10, v14
	v_mul_f32_e32 v9, v9, v14
	v_mul_f32_e32 v8, v8, v14
	v_mul_f32_e32 v7, v7, v14
	v_mul_f32_e32 v6, v6, v14
	v_mul_f32_e32 v16, v55, v16
	v_mul_f32_e32 v12, v54, v12
	v_mul_f32_e32 v11, v53, v11
	v_mul_f32_e32 v10, v52, v10
	v_mul_f32_e32 v9, v51, v9
	v_mul_f32_e32 v8, v50, v8
	v_mul_f32_e32 v7, v49, v7
	v_mul_f32_e32 v6, v48, v6
	v_cvt_pk_bf16_f32 v16, v16, s0
	v_cvt_pk_bf16_f32 v12, v12, s0
	v_cvt_pk_bf16_f32 v11, v11, s0
	v_cvt_pk_bf16_f32 v10, v10, s0
	v_cvt_pk_bf16_f32 v9, v9, s0
	v_cvt_pk_bf16_f32 v8, v8, s0
	v_cvt_pk_bf16_f32 v7, v7, s0
	v_cvt_pk_bf16_f32 v6, v6, s0
	global_store_short v[4:5], v16, off
	global_store_short v[4:5], v12, off offset:32
	global_store_short v[4:5], v11, off offset:64
	global_store_short v[4:5], v10, off offset:96
	global_store_short v[4:5], v9, off offset:128
	global_store_short v[4:5], v8, off offset:160
	global_store_short v[4:5], v7, off offset:192
	global_store_short v[4:5], v6, off offset:224
	s_barrier
	s_cbranch_scc1 .LBB0_632
